# window loop rescale test reduced to one compare against a per-lane selected threshold; static s_setprio 1 for waves 4-7 during attention items
# baseline (speedup 1.0000x reference)
.LBB0_857:
	s_setprio 0
	s_barrier
	s_and_saveexec_b64 s[28:29], s[8:9]
	s_cbranch_execz .LBB0_861
	s_mov_b64 s[30:31], exec
	v_mbcnt_lo_u32_b32 v0, s30, 0
	v_mbcnt_hi_u32_b32 v0, s31, v0
	v_cmp_eq_u32_e32 vcc, 0, v0
	s_and_saveexec_b64 s[6:7], vcc
	s_cbranch_execz .LBB0_860
	s_bcnt1_i32_b64 s10, s[30:31]
	v_mov_b32_e32 v2, s10
	global_atomic_add v2, v1, v2, s[20:21] sc0

.LBB0_1057:
	s_andn2_b64 vcc, exec, s[6:7]
	s_cbranch_vccnz .LBB0_1255
	s_add_i32 s6, s24, 0xffffffa0
	v_mov_b32_e32 v218, v203
	s_and_b32 s50, s6, 0xff
	s_xor_b32 s25, s50, 0xff
	v_readfirstlane_b32 s79, v218
	s_ashr_i32 s78, s79, 6
	s_cmp_ge_i32 s78, 4
	s_cbranch_scc0 .Lnsa_prio_skip
	s_setprio 1
.Lnsa_prio_skip:
	s_lshl_b32 s27, s25, 6
	s_lshl_b32 s26, s78, 3
	v_bfe_u32 v217, v218, 2, 2
	s_add_i32 s26, s26, s27
	s_lshr_b32 s68, s6, 8
	v_and_b32_e32 v219, 3, v218
	v_or_b32_e32 v77, s26, v217
	v_lshl_or_b32 v79, s68, 2, v219
	v_mov_b64_e32 v[6:7], s[88:89]
	v_or_b32_e32 v76, 4, v77
	v_mad_i64_i32 v[64:65], s[6:7], v77, s63, v[6:7]
	v_lshlrev_b32_e32 v0, 7, v79
	v_mad_i64_i32 v[62:63], s[6:7], v76, s63, v[6:7]
	v_lshl_add_u64 v[2:3], v[64:65], 0, v[0:1]
	v_and_b32_e32 v8, 48, v218
	v_mov_b32_e32 v9, v1
	v_lshl_add_u64 v[6:7], v[62:63], 0, v[0:1]
	v_lshl_add_u64 v[172:173], v[2:3], 0, v[8:9]
	v_lshl_add_u64 v[174:175], v[6:7], 0, v[8:9]
	global_load_dwordx4 v[14:17], v[172:173], off offset:3072
	global_load_dwordx4 v[2:5], v[172:173], off offset:3136
	global_load_dwordx4 v[10:13], v[174:175], off offset:3072
	global_load_dwordx4 v[6:9], v[174:175], off offset:3136
	s_lshl_b64 s[6:7], s[68:69], 17
	v_readlane_b32 s10, v249, 42
	v_mov_b32_e32 v0, v218
	s_add_u32 s28, s10, s6
	v_readlane_b32 s10, v249, 43
	s_addc_u32 s29, s10, s7
	v_ashrrev_i32_e32 v20, 3, v0
	v_readlane_b32 s10, v249, 32
	v_and_b32_e32 v18, 7, v0
	v_lshrrev_b32_e32 v19, 4, v0
	v_lshrrev_b32_e32 v21, 3, v20
	s_add_u32 s30, s10, s6
	v_readlane_b32 s6, v249, 33
	v_xor_b32_e32 v22, v19, v0
	v_bfe_u32 v19, v20, 1, 3
	v_bitop3_b32 v18, v21, v18, 2 bitop3:0x6c
	v_ashrrev_i32_e32 v21, 31, v20
	s_addc_u32 s31, s6, s7
	v_xor_b32_e32 v23, v18, v19
	v_readfirstlane_b32 s6, v0
	v_lshlrev_b64 v[18:19], 11, v[20:21]
	v_lshlrev_b32_e32 v0, 4, v22
	v_lshl_add_u64 v[18:19], s[28:29], 0, v[18:19]
	v_and_b32_e32 v0, 0x70, v0
	v_lshl_add_u64 v[24:25], v[18:19], 0, v[0:1]
	v_min_i32_e32 v18, 0x3ff, v20
	v_ashrrev_i32_e32 v19, 31, v18
	s_lshl_b32 s6, s6, 4
	v_lshlrev_b64 v[18:19], 7, v[18:19]
	s_and_b32 s10, s6, 0xfffffc00
	v_lshl_add_u64 v[18:19], s[30:31], 0, v[18:19]
	v_lshlrev_b32_e32 v0, 4, v23
	s_add_i32 s10, s10, 0
	v_lshl_add_u64 v[18:19], v[18:19], 0, v[0:1]
	s_mov_b32 s6, m0
	s_mov_b32 m0, s10
	s_nop 0
	global_load_lds_dwordx4 v[18:19], off
	s_mov_b32 m0, s6
	s_add_i32 s11, s10, 0x2000
	s_mov_b32 s6, m0
	s_mov_b32 m0, s11
	s_nop 0
	global_load_lds_dwordx4 v[24:25], off
	s_mov_b32 m0, s6
	v_lshlrev_b32_e32 v21, 3, v23
	s_cmp_gt_u32 s25, 15
	s_cselect_b64 s[34:35], -1, 0
	s_cmp_lt_u32 s25, 16
	v_lshlrev_b32_e32 v0, 1, v21
	s_cbranch_scc1 .LBB0_1060
	v_min_i32_e32 v18, 0x3bf, v20
	v_ashrrev_i32_e32 v19, 31, v18
	v_lshlrev_b64 v[18:19], 7, v[18:19]
	v_lshl_add_u64 v[18:19], s[30:31], 0, v[18:19]
	v_lshl_add_u64 v[18:19], v[18:19], 0, v[0:1]
	s_mov_b64 s[6:7], 0x2000
	v_lshl_add_u64 v[18:19], v[18:19], 0, s[6:7]
	s_add_i32 s6, s10, 0x4000
	s_mov_b32 s7, m0
	s_mov_b32 m0, s6
	s_nop 0
	global_load_lds_dwordx4 v[18:19], off
	s_mov_b32 m0, s7
	v_lshl_add_u64 v[18:19], v[24:25], 0, s[80:81]
	s_add_i32 s6, s10, 0x6000
	s_mov_b32 s7, m0
	s_mov_b32 m0, s6
	s_nop 0
	global_load_lds_dwordx4 v[18:19], off
	s_mov_b32 m0, s7

.LBB0_1223:
	s_add_i32 s6, s26, 0
	s_cmp_le_u32 s27, s54
	s_cselect_b64 s[10:11], -1, 0
	s_xor_b64 s[12:13], s[28:29], -1
	s_or_b64 s[48:49], s[10:11], s[12:13]
	v_add_u32_e32 v91, 0xfffffdfb, v110
	v_add_u32_e32 v90, 0xfffffdfa, v110
	v_add_u32_e32 v89, 0xfffffdf9, v110
	v_add_u32_e32 v88, 0xfffffddc, v110
	v_add_u32_e32 v87, 0xfffffddb, v110
	v_add_u32_e32 v86, 0xfffffdda, v110
	v_add_u32_e32 v85, 0xfffffdd9, v110
	s_mov_b64 s[52:53], -1
	s_and_b64 vcc, exec, s[48:49]
	v_cmp_ge_f32_e64 s[28:29], s76, v92
	v_add_u32_e32 v84, s6, v163
	v_add_u32_e32 v3, s6, v211
	v_add_u32_e32 v2, s6, v165
	v_add_u32_e32 v0, s6, v212
	v_cmp_lt_u32_e64 s[44:45], s77, v91
	v_cmp_lt_u32_e64 s[40:41], s77, v90
	v_cmp_lt_u32_e64 s[42:43], s77, v89
	v_cmp_lt_u32_e64 s[30:31], s77, v88
	v_cmp_lt_u32_e64 s[34:35], s77, v87
	v_cmp_lt_u32_e64 s[36:37], s77, v86
	v_cmp_lt_u32_e64 s[38:39], s77, v85
	s_cbranch_vccz .LBB0_1235
	ds_read_b128 v[134:137], v84
	ds_read_b128 v[138:141], v3
	ds_read_b128 v[142:145], v2
	ds_read_b128 v[170:173], v0
	ds_read_b128 v[174:177], v84 offset:4096
	ds_read_b128 v[182:185], v3 offset:4096
	ds_read_b128 v[186:189], v2 offset:4096
	ds_read_b128 v[206:209], v0 offset:4096
	s_waitcnt lgkmcnt(8)
	s_nop 0
	v_cndmask_b32_e64 v36, v92, 0, s[28:29]
	v_xor_b32_e32 v38, 0x80000000, v36
	v_mov_b32_e32 v39, v38
	v_mov_b32_e32 v40, v38
	v_mov_b32_e32 v41, v38
	v_add_u32_e32 v37, -4, v110
	s_movk_i32 s7, 0x200
	s_waitcnt vmcnt(3)
	s_waitcnt lgkmcnt(7)
	v_mfma_f32_16x16x32_bf16 v[42:45], v[134:137], v[4:7], v[38:41]
	v_cmp_gt_u32_e32 vcc, s7, v37
	v_add_u32_e32 v37, 0xfffffdf8, v110
	s_waitcnt vmcnt(2)
	s_waitcnt lgkmcnt(6)
	v_mfma_f32_16x16x32_bf16 v[42:45], v[138:141], v[8:11], v[42:45]
	s_nop 0
	s_nop 0
	s_nop 0
	s_waitcnt lgkmcnt(5)
	v_mfma_f32_16x16x32_bf16 v[46:49], v[142:145], v[4:7], v[38:41]
	s_nop 0
	s_waitcnt lgkmcnt(4)
	v_mfma_f32_16x16x32_bf16 v[46:49], v[170:173], v[8:11], v[46:49]
	s_nop 0
	s_nop 0
	s_nop 0
	s_waitcnt lgkmcnt(3)
	v_mfma_f32_16x16x32_bf16 v[50:53], v[174:177], v[4:7], v[38:41]
	s_nop 0
	s_waitcnt lgkmcnt(2)
	v_mfma_f32_16x16x32_bf16 v[60:63], v[182:185], v[8:11], v[50:53]
	s_nop 5
	s_nop 0
	s_nop 0
	v_cndmask_b32_e64 v61, v201, v61, s[34:35]
	s_nop 0
	s_waitcnt lgkmcnt(1)
	v_mfma_f32_16x16x32_bf16 v[38:41], v[186:189], v[4:7], v[38:41]
	v_cndmask_b32_e32 v52, v201, v42, vcc
	v_cmp_lt_u32_e32 vcc, s77, v37
	v_add_u32_e32 v37, 0xfffffdf7, v110
	s_nop 0
	s_waitcnt lgkmcnt(0)
	v_mfma_f32_16x16x32_bf16 v[38:41], v[206:209], v[8:11], v[38:41]
	v_cndmask_b32_e32 v56, v201, v46, vcc
	v_cmp_lt_u32_e32 vcc, s77, v37
	v_add_u32_e32 v37, 0xfffffdf6, v110
	v_cndmask_b32_e64 v54, v201, v44, s[40:41]
	v_cndmask_b32_e32 v57, v201, v47, vcc
	v_cmp_lt_u32_e32 vcc, s77, v37
	v_add_u32_e32 v37, 0xfffffdf5, v110
	v_cndmask_b32_e64 v55, v201, v45, s[42:43]
	v_cndmask_b32_e32 v58, v201, v48, vcc
	v_cmp_lt_u32_e32 vcc, s77, v37
	v_add_u32_e32 v37, 0xfffffdd8, v110
	v_cndmask_b32_e64 v53, v201, v43, s[44:45]
	v_cndmask_b32_e32 v59, v201, v49, vcc
	v_cmp_lt_u32_e32 vcc, s77, v37
	v_add_u32_e32 v37, 0xfffffdd7, v110
	v_cndmask_b32_e64 v62, v201, v62, s[36:37]
	v_cndmask_b32_e32 v64, v201, v38, vcc
	v_cmp_lt_u32_e32 vcc, s77, v37
	v_add_u32_e32 v37, 0xfffffdd6, v110
	v_max_f32_e32 v38, v54, v54
	v_cndmask_b32_e32 v65, v201, v39, vcc
	v_cmp_lt_u32_e32 vcc, s77, v37
	v_add_u32_e32 v37, 0xfffffdd5, v110
	v_cndmask_b32_e64 v63, v201, v63, s[38:39]
	v_cndmask_b32_e32 v66, v201, v40, vcc
	v_cmp_lt_u32_e32 vcc, s77, v37
	v_max_f32_e32 v37, v55, v55
	v_max_f32_e32 v37, v38, v37
	v_max3_f32 v37, v52, v53, v37
	v_max3_f32 v38, v57, v58, v59
	v_cndmask_b32_e64 v60, v201, v60, s[30:31]
	v_cndmask_b32_e32 v67, v201, v41, vcc
	v_max3_f32 v37, v37, v56, v38
	v_max3_f32 v38, v61, v62, v63
	v_max3_f32 v37, v37, v60, v38
	v_mov_b32_e32 v246, s76
	v_mov_b32_e32 v247, s82
	v_cndmask_b32_e64 v245, v247, v246, s[28:29]
	v_max3_f32 v38, v65, v66, v67
	v_max3_f32 v37, v37, v64, v38
	v_cmp_lt_f32_e32 vcc, v245, v37
	s_cbranch_vccz .LBB0_1247
	v_mov_b32_e32 v38, v37
	s_nop 1
	v_permlane16_swap_b32_e32 v37, v38
	v_max_f32_e32 v38, v38, v38
	v_max_f32_e32 v37, v37, v37
	v_max_f32_e32 v37, v37, v38
	v_mov_b32_e32 v38, v37
	s_nop 1
	v_permlane32_swap_b32_e32 v37, v38
	v_max_f32_e32 v38, v38, v38
	v_max_f32_e32 v37, v37, v37
	v_max_f32_e32 v37, v37, v38
	v_cmp_ge_f32_e32 vcc, s76, v37
	s_and_b64 vcc, s[28:29], vcc
	s_nop 0
	v_cndmask_b32_e64 v38, v37, 0, vcc
	v_max_f32_e32 v37, 0, v37
	v_cndmask_b32_e64 v123, v37, v38, s[28:29]
	v_exp_f32_e64 v96, -v123
	v_add_f32_e32 v36, v36, v123
	v_cndmask_b32_e32 v114, v36, v92, vcc
	v_sub_f32_e32 v95, v52, v123
	v_mul_f32_e32 v94, v93, v96
	v_pk_mul_f32 v[50:51], v[82:83], v[96:97] op_sel_hi:[1,0]
	v_pk_mul_f32 v[48:49], v[80:81], v[96:97] op_sel_hi:[1,0]
	v_pk_mul_f32 v[46:47], v[78:79], v[96:97] op_sel_hi:[1,0]
	v_pk_mul_f32 v[44:45], v[76:77], v[96:97] op_sel_hi:[1,0]
	v_pk_mul_f32 v[42:43], v[74:75], v[96:97] op_sel_hi:[1,0]
	v_pk_mul_f32 v[40:41], v[72:73], v[96:97] op_sel_hi:[1,0]
	v_pk_mul_f32 v[38:39], v[70:71], v[96:97] op_sel_hi:[1,0]
	v_pk_mul_f32 v[36:37], v[68:69], v[96:97] op_sel_hi:[1,0]
	v_sub_f32_e32 v96, v53, v123
	v_sub_f32_e32 v97, v54, v123
	v_sub_f32_e32 v98, v55, v123
	v_sub_f32_e32 v99, v56, v123
	v_sub_f32_e32 v108, v57, v123
	v_sub_f32_e32 v109, v58, v123
	v_sub_f32_e32 v115, v59, v123
	v_sub_f32_e32 v116, v60, v123
	v_sub_f32_e32 v117, v61, v123
	v_sub_f32_e32 v118, v62, v123
	v_sub_f32_e32 v119, v63, v123
	v_sub_f32_e32 v120, v64, v123
	v_sub_f32_e32 v121, v65, v123
	v_sub_f32_e32 v122, v66, v123
	v_sub_f32_e32 v123, v67, v123
	s_cbranch_execnz .LBB0_1227

.LBB0_1229:
	ds_read_b128 v[134:137], v84
	ds_read_b128 v[138:141], v3
	ds_read_b128 v[142:145], v2
	ds_read_b128 v[170:173], v0
	ds_read_b128 v[174:177], v84 offset:4096
	ds_read_b128 v[182:185], v3 offset:4096
	ds_read_b128 v[186:189], v2 offset:4096
	ds_read_b128 v[206:209], v0 offset:4096
	s_waitcnt lgkmcnt(8)
	s_nop 0
	s_nop 0
	s_nop 0
	v_cndmask_b32_e64 v68, v112, 0, s[28:29]
	v_xor_b32_e32 v78, 0x80000000, v68
	v_mov_b32_e32 v79, v78
	v_mov_b32_e32 v80, v78
	v_mov_b32_e32 v81, v78
	s_movk_i32 s7, 0x200
	v_cmp_gt_u32_e32 vcc, s7, v110
	s_waitcnt vmcnt(1)
	s_waitcnt lgkmcnt(7)
	v_mfma_f32_16x16x32_bf16 v[70:73], v[134:137], v[12:15], v[78:81]
	v_add_u32_e32 v69, 0xfffffdff, v110
	s_nop 0
	s_waitcnt lgkmcnt(5)
	v_mfma_f32_16x16x32_bf16 v[74:77], v[142:145], v[12:15], v[78:81]
	s_waitcnt vmcnt(0)
	v_mfma_f32_16x16x32_bf16 v[70:73], v[138:141], v[16:19], v[70:73]
	s_nop 0
	s_nop 0
	s_nop 0
	s_waitcnt lgkmcnt(4)
	v_mfma_f32_16x16x32_bf16 v[74:77], v[170:173], v[16:19], v[74:77]
	s_nop 0
	s_nop 0
	s_nop 0
	s_waitcnt lgkmcnt(3)
	v_mfma_f32_16x16x32_bf16 v[124:127], v[174:177], v[12:15], v[78:81]
	v_cndmask_b32_e32 v92, v201, v70, vcc
	v_cmp_lt_u32_e32 vcc, s77, v69
	v_add_u32_e32 v69, 0xfffffdfe, v110
	s_nop 0
	s_waitcnt lgkmcnt(2)
	v_mfma_f32_16x16x32_bf16 v[116:119], v[182:185], v[16:19], v[124:127]
	v_cndmask_b32_e32 v93, v201, v71, vcc
	v_cmp_lt_u32_e32 vcc, s77, v69
	v_add_u32_e32 v69, 0xfffffdfd, v110
	s_nop 0
	s_waitcnt lgkmcnt(1)
	v_mfma_f32_16x16x32_bf16 v[78:81], v[186:189], v[12:15], v[78:81]
	v_cndmask_b32_e32 v94, v201, v72, vcc
	v_cmp_lt_u32_e32 vcc, s77, v69
	v_add_u32_e32 v69, 0xfffffdfc, v110
	s_nop 0
	s_waitcnt lgkmcnt(0)
	v_mfma_f32_16x16x32_bf16 v[78:81], v[206:209], v[16:19], v[78:81]
	v_cndmask_b32_e32 v95, v201, v73, vcc
	v_cmp_lt_u32_e32 vcc, s77, v69
	v_add_u32_e32 v69, 0xfffffde0, v110
	v_max_f32_e32 v70, v94, v94
	v_cndmask_b32_e32 v96, v201, v74, vcc
	v_cmp_lt_u32_e32 vcc, s77, v91
	s_nop 1
	v_cndmask_b32_e32 v91, v201, v75, vcc
	v_cmp_lt_u32_e32 vcc, s77, v90
	s_nop 1
	v_cndmask_b32_e32 v90, v201, v76, vcc
	v_cmp_lt_u32_e32 vcc, s77, v89
	s_nop 1
	v_cndmask_b32_e32 v89, v201, v77, vcc
	v_cmp_lt_u32_e32 vcc, s77, v69
	v_add_u32_e32 v69, 0xfffffddf, v110
	s_nop 0
	v_cndmask_b32_e32 v97, v201, v116, vcc
	v_cmp_lt_u32_e32 vcc, s77, v69
	v_add_u32_e32 v69, 0xfffffdde, v110
	s_nop 0
	v_cndmask_b32_e32 v98, v201, v117, vcc
	v_cmp_lt_u32_e32 vcc, s77, v69
	v_add_u32_e32 v69, 0xfffffddd, v110
	s_nop 0
	v_cndmask_b32_e32 v99, v201, v118, vcc
	v_cmp_lt_u32_e32 vcc, s77, v69
	v_max_f32_e32 v69, v95, v95
	v_max_f32_e32 v69, v70, v69
	v_cndmask_b32_e32 v108, v201, v119, vcc
	v_cmp_lt_u32_e32 vcc, s77, v88
	v_max3_f32 v69, v92, v93, v69
	v_max3_f32 v70, v91, v90, v89
	v_cndmask_b32_e32 v88, v201, v78, vcc
	v_cmp_lt_u32_e32 vcc, s77, v87
	v_max3_f32 v69, v69, v96, v70
	v_max3_f32 v70, v98, v99, v108
	v_cndmask_b32_e32 v87, v201, v79, vcc
	v_cmp_lt_u32_e32 vcc, s77, v86
	v_max3_f32 v69, v69, v97, v70
	s_nop 0
	v_cndmask_b32_e32 v86, v201, v80, vcc
	v_cmp_lt_u32_e32 vcc, s77, v85
	s_nop 1
	v_cndmask_b32_e32 v85, v201, v81, vcc
	v_mov_b32_e32 v246, s76
	v_mov_b32_e32 v247, s82
	v_cndmask_b32_e64 v245, v247, v246, s[28:29]
	v_max3_f32 v70, v87, v86, v85
	v_max3_f32 v69, v69, v88, v70
	v_cmp_lt_f32_e32 vcc, v245, v69
	s_cbranch_vccz .LBB0_1248
	v_mov_b32_e32 v70, v69
	s_nop 1
	v_permlane16_swap_b32_e32 v69, v70
	v_max_f32_e32 v70, v70, v70
	v_max_f32_e32 v69, v69, v69
	v_max_f32_e32 v69, v69, v70
	v_mov_b32_e32 v70, v69
	s_nop 1
	v_permlane32_swap_b32_e32 v69, v70
	v_max_f32_e32 v70, v70, v70
	v_max_f32_e32 v69, v69, v69
	v_max_f32_e32 v69, v69, v70
	v_cmp_ge_f32_e32 vcc, s76, v69
	s_and_b64 vcc, s[28:29], vcc
	s_nop 0
	v_cndmask_b32_e64 v70, v69, 0, vcc
	v_max_f32_e32 v69, 0, v69
	v_cndmask_b32_e64 v132, v69, v70, s[28:29]
	v_exp_f32_e64 v118, -v132
	v_add_f32_e32 v68, v68, v132
	v_cndmask_b32_e32 v115, v68, v112, vcc
	v_sub_f32_e32 v117, v92, v132
	v_mul_f32_e32 v116, v113, v118
	v_pk_mul_f32 v[82:83], v[34:35], v[118:119] op_sel_hi:[1,0]
	v_pk_mul_f32 v[80:81], v[32:33], v[118:119] op_sel_hi:[1,0]
	v_pk_mul_f32 v[78:79], v[30:31], v[118:119] op_sel_hi:[1,0]
	v_pk_mul_f32 v[76:77], v[28:29], v[118:119] op_sel_hi:[1,0]
	v_pk_mul_f32 v[74:75], v[26:27], v[118:119] op_sel_hi:[1,0]
	v_pk_mul_f32 v[72:73], v[24:25], v[118:119] op_sel_hi:[1,0]
	v_pk_mul_f32 v[70:71], v[22:23], v[118:119] op_sel_hi:[1,0]
	v_pk_mul_f32 v[68:69], v[20:21], v[118:119] op_sel_hi:[1,0]
	v_sub_f32_e32 v118, v93, v132
	v_sub_f32_e32 v119, v94, v132
	v_sub_f32_e32 v120, v95, v132
	v_sub_f32_e32 v121, v96, v132
	v_sub_f32_e32 v122, v91, v132
	v_sub_f32_e32 v123, v90, v132
	v_sub_f32_e32 v124, v89, v132
	v_sub_f32_e32 v125, v97, v132
	v_sub_f32_e32 v126, v98, v132
	v_sub_f32_e32 v127, v99, v132
	v_sub_f32_e32 v128, v108, v132
	v_sub_f32_e32 v129, v88, v132
	v_sub_f32_e32 v130, v87, v132
	v_sub_f32_e32 v131, v86, v132
	v_sub_f32_e32 v132, v85, v132
	s_cbranch_execnz .LBB0_1232

.LBB0_1235:
	s_and_b64 vcc, exec, s[52:53]
	s_cbranch_vccz .LBB0_1228
	ds_read_b128 v[134:137], v84
	ds_read_b128 v[138:141], v3
	ds_read_b128 v[142:145], v2
	ds_read_b128 v[170:173], v0
	ds_read_b128 v[174:177], v84 offset:4096
	ds_read_b128 v[182:185], v3 offset:4096
	ds_read_b128 v[186:189], v2 offset:4096
	s_waitcnt lgkmcnt(7)
	s_nop 0
	v_cmp_ge_f32_e64 s[28:29], s76, v92
	s_nop 0
	s_nop 0
	v_cndmask_b32_e64 v36, v92, 0, s[28:29]
	v_xor_b32_e32 v46, 0x80000000, v36
	v_mov_b32_e32 v47, v46
	v_mov_b32_e32 v48, v46
	v_mov_b32_e32 v49, v46
	s_waitcnt vmcnt(3)
	s_nop 0
	s_waitcnt lgkmcnt(6)
	v_mfma_f32_16x16x32_bf16 v[38:41], v[134:137], v[4:7], v[46:49]
	s_waitcnt vmcnt(2)
	s_waitcnt lgkmcnt(5)
	v_mfma_f32_16x16x32_bf16 v[52:55], v[138:141], v[8:11], v[38:41]
	s_nop 0
	s_waitcnt lgkmcnt(4)
	v_mfma_f32_16x16x32_bf16 v[42:45], v[142:145], v[4:7], v[46:49]
	s_nop 3
	s_nop 0
	s_nop 0
	v_max_f32_e32 v37, v55, v55
	v_max_f32_e32 v50, v54, v54
	s_nop 0
	s_waitcnt lgkmcnt(3)
	v_mfma_f32_16x16x32_bf16 v[56:59], v[170:173], v[8:11], v[42:45]
	s_nop 2
	s_nop 0
	s_nop 0
	ds_read_b128 v[94:97], v0 offset:4096
	s_nop 0
	v_max_f32_e32 v37, v50, v37
	s_nop 0
	s_waitcnt lgkmcnt(3)
	v_mfma_f32_16x16x32_bf16 v[38:41], v[174:177], v[4:7], v[46:49]
	v_max3_f32 v37, v52, v53, v37
	s_nop 0
	s_waitcnt lgkmcnt(2)
	v_mfma_f32_16x16x32_bf16 v[60:63], v[182:185], v[8:11], v[38:41]
	v_max3_f32 v42, v57, v58, v59
	v_max3_f32 v37, v37, v56, v42
	s_nop 0
	s_waitcnt lgkmcnt(1)
	v_mfma_f32_16x16x32_bf16 v[38:41], v[186:189], v[4:7], v[46:49]
	s_nop 0
	s_waitcnt lgkmcnt(0)
	v_mfma_f32_16x16x32_bf16 v[64:67], v[94:97], v[8:11], v[38:41]
	s_nop 1
	v_max3_f32 v42, v61, v62, v63
	v_max3_f32 v37, v37, v60, v42
	s_nop 3
	v_mov_b32_e32 v246, s76
	v_mov_b32_e32 v247, s82
	v_cndmask_b32_e64 v245, v247, v246, s[28:29]
	v_max3_f32 v38, v65, v66, v67
	v_max3_f32 v37, v37, v64, v38
	v_cmp_lt_f32_e32 vcc, v245, v37
	s_cbranch_vccz .LBB0_1249
	v_mov_b32_e32 v38, v37
	s_nop 1
	v_permlane16_swap_b32_e32 v37, v38
	v_max_f32_e32 v38, v38, v38
	v_max_f32_e32 v37, v37, v37
	v_max_f32_e32 v37, v37, v38
	v_mov_b32_e32 v38, v37
	s_nop 1
	v_permlane32_swap_b32_e32 v37, v38
	v_max_f32_e32 v38, v38, v38
	v_max_f32_e32 v37, v37, v37
	v_max_f32_e32 v37, v37, v38
	v_cmp_ge_f32_e32 vcc, s76, v37
	s_and_b64 vcc, s[28:29], vcc
	s_nop 0
	v_cndmask_b32_e64 v38, v37, 0, vcc
	v_max_f32_e32 v37, 0, v37
	v_cndmask_b32_e64 v123, v37, v38, s[28:29]
	v_exp_f32_e64 v96, -v123
	v_add_f32_e32 v36, v36, v123
	v_cndmask_b32_e32 v114, v36, v92, vcc
	v_sub_f32_e32 v95, v52, v123
	v_mul_f32_e32 v94, v93, v96
	v_pk_mul_f32 v[50:51], v[82:83], v[96:97] op_sel_hi:[1,0]
	v_pk_mul_f32 v[48:49], v[80:81], v[96:97] op_sel_hi:[1,0]
	v_pk_mul_f32 v[46:47], v[78:79], v[96:97] op_sel_hi:[1,0]
	v_pk_mul_f32 v[44:45], v[76:77], v[96:97] op_sel_hi:[1,0]
	v_pk_mul_f32 v[42:43], v[74:75], v[96:97] op_sel_hi:[1,0]
	v_pk_mul_f32 v[40:41], v[72:73], v[96:97] op_sel_hi:[1,0]
	v_pk_mul_f32 v[38:39], v[70:71], v[96:97] op_sel_hi:[1,0]
	v_pk_mul_f32 v[36:37], v[68:69], v[96:97] op_sel_hi:[1,0]
	v_sub_f32_e32 v96, v53, v123
	v_sub_f32_e32 v97, v54, v123
	v_sub_f32_e32 v98, v55, v123
	v_sub_f32_e32 v99, v56, v123
	v_sub_f32_e32 v108, v57, v123
	v_sub_f32_e32 v109, v58, v123
	v_sub_f32_e32 v115, v59, v123
	v_sub_f32_e32 v116, v60, v123
	v_sub_f32_e32 v117, v61, v123
	v_sub_f32_e32 v118, v62, v123
	v_sub_f32_e32 v119, v63, v123
	v_sub_f32_e32 v120, v64, v123
	v_sub_f32_e32 v121, v65, v123
	v_sub_f32_e32 v122, v66, v123
	v_sub_f32_e32 v123, v67, v123
	s_cbranch_execnz .LBB0_1239

.LBB0_1240:
	s_and_b64 vcc, exec, s[30:31]
	s_cbranch_vccz .LBB0_1245
	ds_read_b128 v[134:137], v84
	ds_read_b128 v[138:141], v3
	ds_read_b128 v[142:145], v2
	ds_read_b128 v[170:173], v0
	ds_read_b128 v[174:177], v84 offset:4096
	ds_read_b128 v[182:185], v3 offset:4096
	ds_read_b128 v[186:189], v2 offset:4096
	ds_read_b128 v[206:209], v0 offset:4096
	s_waitcnt lgkmcnt(8)
	s_nop 0
	v_cmp_ge_f32_e64 s[28:29], s76, v112
	s_nop 0
	s_nop 0
	v_cndmask_b32_e64 v85, v112, 0, s[28:29]
	v_xor_b32_e32 v80, 0x80000000, v85
	v_mov_b32_e32 v81, v80
	v_mov_b32_e32 v82, v80
	v_mov_b32_e32 v83, v80
	s_waitcnt vmcnt(1)
	s_nop 0
	s_waitcnt lgkmcnt(7)
	v_mfma_f32_16x16x32_bf16 v[68:71], v[134:137], v[12:15], v[80:83]
	s_waitcnt vmcnt(0)
	s_waitcnt lgkmcnt(6)
	v_mfma_f32_16x16x32_bf16 v[68:71], v[138:141], v[16:19], v[68:71]
	s_nop 0
	s_nop 0
	s_waitcnt lgkmcnt(5)
	v_mfma_f32_16x16x32_bf16 v[72:75], v[142:145], v[12:15], v[80:83]
	s_nop 0
	s_waitcnt lgkmcnt(4)
	v_mfma_f32_16x16x32_bf16 v[72:75], v[170:173], v[16:19], v[72:75]
	s_nop 0
	s_nop 0
	s_nop 0
	v_max_f32_e32 v0, v71, v71
	s_nop 0
	s_waitcnt lgkmcnt(3)
	v_mfma_f32_16x16x32_bf16 v[76:79], v[174:177], v[12:15], v[80:83]
	v_max_f32_e32 v2, v70, v70
	v_max_f32_e32 v0, v2, v0
	v_max3_f32 v0, v68, v69, v0
	s_nop 0
	s_waitcnt lgkmcnt(1)
	v_mfma_f32_16x16x32_bf16 v[80:83], v[186:189], v[12:15], v[80:83]
	v_max3_f32 v2, v73, v74, v75
	v_max3_f32 v0, v0, v72, v2
	v_mfma_f32_16x16x32_bf16 v[76:79], v[182:185], v[16:19], v[76:79]
	s_nop 0
	s_waitcnt lgkmcnt(0)
	v_mfma_f32_16x16x32_bf16 v[80:83], v[206:209], v[16:19], v[80:83]
	s_nop 5
	v_max3_f32 v2, v77, v78, v79
	v_max3_f32 v0, v0, v76, v2
	v_mov_b32_e32 v246, s76
	v_mov_b32_e32 v247, s82
	v_cndmask_b32_e64 v245, v247, v246, s[28:29]
	v_max3_f32 v2, v81, v82, v83
	v_max3_f32 v0, v0, v80, v2
	v_cmp_lt_f32_e32 vcc, v245, v0
	s_cbranch_vccz .LBB0_1250
	v_mov_b32_e32 v2, v0
	s_nop 1
	v_permlane16_swap_b32_e32 v0, v2
	v_max_f32_e32 v2, v2, v2
	v_max_f32_e32 v0, v0, v0
	v_max_f32_e32 v0, v0, v2
	v_mov_b32_e32 v2, v0
	s_nop 1
	v_permlane32_swap_b32_e32 v0, v2
	v_max_f32_e32 v2, v2, v2
	v_max_f32_e32 v0, v0, v0
	v_max_f32_e32 v0, v0, v2
	v_cmp_ge_f32_e32 vcc, s76, v0
	s_and_b64 vcc, s[28:29], vcc
	s_nop 0
	v_cndmask_b32_e64 v2, v0, 0, vcc
	v_max_f32_e32 v0, 0, v0
	v_cndmask_b32_e64 v3, v0, v2, s[28:29]
	v_exp_f32_e64 v2, -v3
	v_add_f32_e32 v0, v85, v3
	v_cndmask_b32_e32 v115, v0, v112, vcc
	v_sub_f32_e32 v108, v68, v3
	v_mul_f32_e32 v0, v113, v2
	v_pk_mul_f32 v[86:87], v[34:35], v[2:3] op_sel_hi:[1,0]
	v_pk_mul_f32 v[84:85], v[32:33], v[2:3] op_sel_hi:[1,0]
	v_pk_mul_f32 v[90:91], v[30:31], v[2:3] op_sel_hi:[1,0]
	v_pk_mul_f32 v[88:89], v[28:29], v[2:3] op_sel_hi:[1,0]
	v_pk_mul_f32 v[98:99], v[26:27], v[2:3] op_sel_hi:[1,0]
	v_pk_mul_f32 v[96:97], v[24:25], v[2:3] op_sel_hi:[1,0]
	v_pk_mul_f32 v[94:95], v[22:23], v[2:3] op_sel_hi:[1,0]
	v_pk_mul_f32 v[92:93], v[20:21], v[2:3] op_sel_hi:[1,0]
	v_sub_f32_e32 v116, v69, v3
	v_sub_f32_e32 v117, v70, v3
	v_sub_f32_e32 v118, v71, v3
	v_sub_f32_e32 v119, v72, v3
	v_sub_f32_e32 v120, v73, v3
	v_sub_f32_e32 v121, v74, v3
	v_sub_f32_e32 v122, v75, v3
	v_sub_f32_e32 v123, v76, v3
	v_sub_f32_e32 v124, v77, v3
	v_sub_f32_e32 v125, v78, v3
	v_sub_f32_e32 v126, v79, v3
	v_sub_f32_e32 v127, v80, v3
	v_sub_f32_e32 v128, v81, v3
	v_sub_f32_e32 v2, v82, v3
	v_sub_f32_e32 v3, v83, v3
	s_cbranch_execnz .LBB0_1244
